# output-gate phase loop software-pipelined two tokens ahead (unrolled by two, two prefetch register sets), on top of the one-to-all flag version
# speedup vs baseline: 1.0268x; 1.0071x over previous
; __device__ __forceinline__ void unpack8(const u32x4 w, float (&f)[8]) { f[0] = bf_lo(w.x); f[1] = bf_hi(w.x); f[2] = bf_lo(w.y); f[3] = bf_hi(w.y); f[4] = bf_lo(w.z); f[5] = bf_hi(w.z); f[6] = bf_lo(w.w); f[7] = bf_hi(w.w); }
; __device__ __forceinline__ u32x4 pack8(const float (&f)[8]) { u32x4 o; o.x = pk2(f[0], f[1]); o.y = pk2(f[2], f[3]); o.z = pk2(f[4], f[5]); o.w = pk2(f[6], f[7]); return o; }
; __device__ __forceinline__ float siluf_(float x) { return x * __builtin_amdgcn_rcpf(1.0f + __builtin_amdgcn_exp2f(x * -1.4426950408889634f)); }
; __device__ __forceinline__ void phase_gate(const Args& a) {
;     const int tid = threadIdx.x, lane = tid & 63, wave = tid >> 6;
;     const bf16_t* proj = (const bf16_t*)(a.ws + WS_PROJ); const bf16_t* of = (const bf16_t*)(a.ws + WS_OF2); bf16_t* mix = (bf16_t*)(a.ws + WS_MIX);
;     const float* onw = a.in[6]; const int c0 = (8 * lane) & 127;
;     const f32x4 w0 = *(const f32x4*)(onw + c0), w1 = *(const f32x4*)(onw + c0 + 4);
;     for (int row = blockIdx.x * 8 + wave; row < M; row += gridDim.x * 8) {
;         float of8[8]; unpack8(*(const u32x4*)(of + (size_t)row * 512 + 8 * lane), of8);
;         const f32x4 o0 = {of8[0], of8[1], of8[2], of8[3]}, o1 = {of8[4], of8[5], of8[6], of8[7]};
;         float ss = (o0[0] * o0[0] + o0[1] * o0[1]) + (o0[2] * o0[2] + o0[3] * o0[3]) + (o1[0] * o1[0] + o1[1] * o1[1]) + (o1[2] * o1[2] + o1[3] * o1[3]);
;         ss = sum16(ss); const float r = rsqrtf(ss * (1.0f / 128.0f) + EPS);
;         float z[8]; unpack8(*(const u32x4*)(proj + (size_t)row * NPROJ + 1536 + 8 * lane), z);
;         float y[8];
;         y[0] = o0[0] * r * w0[0] * siluf_(z[0]); y[1] = o0[1] * r * w0[1] * siluf_(z[1]); y[2] = o0[2] * r * w0[2] * siluf_(z[2]); y[3] = o0[3] * r * w0[3] * siluf_(z[3]);
;         y[4] = o1[0] * r * w1[0] * siluf_(z[4]); y[5] = o1[1] * r * w1[1] * siluf_(z[5]); y[6] = o1[2] * r * w1[2] * siluf_(z[6]); y[7] = o1[3] * r * w1[3] * siluf_(z[7]);
;         *(u32x4*)(mix + (size_t)row * 1024 + 8 * lane) = pack8(y);
;     }
.LBB0_583:
	s_or_b64 exec, exec, s[0:1]
	v_readlane_b32 s0, v253, 17
	s_bitcmp0_b32 s0, 5
	s_waitcnt lgkmcnt(0)
	s_barrier
	s_cbranch_scc1 .LBB0_588
	s_waitcnt vmcnt(5)
	v_lshl_add_u32 v8, s82, 3, v153
	s_mov_b32 s0, 0x8000
	v_cmp_gt_i32_e32 vcc, s0, v8
	s_and_saveexec_b64 s[0:1], vcc
	s_cbranch_execz .LBB0_587
	v_lshlrev_b32_e32 v0, 5, v152
	v_readlane_b32 s36, v253, 1
	v_and_b32_e32 v9, 0x1e0, v0
	v_readlane_b32 s48, v253, 13
	v_readlane_b32 s49, v253, 14
	s_nop 4
	global_load_dwordx4 v[0:3], v9, s[48:49]
	global_load_dwordx4 v[4:7], v9, s[48:49] offset:16
	v_lshlrev_b32_e32 v9, 3, v152
	s_waitcnt vmcnt(5)
	v_and_b32_e32 v18, 0x1f8, v9
	v_mov_b32_e32 v11, 0
	v_lshlrev_b32_e32 v10, 1, v18
	s_mov_b64 s[12:13], s[48:49]
	v_lshl_add_u64 v[12:13], s[16:17], 0, v[10:11]
	s_mov_b64 s[4:5], 0x10000000
	v_lshl_add_u64 v[12:13], v[12:13], 0, s[4:5]
	v_lshl_add_u64 v[14:15], s[10:11], 0, v[10:11]
	s_lshl_b32 s8, s80, 3
	s_mov_b64 s[4:5], 0
	s_movk_i32 s9, 0x1400
	v_mov_b64_e32 v[16:17], s[16:17]
	v_lshlrev_b32_e32 v10, 1, v18
	v_mov_b32_e32 v18, 0x358637bd
	s_mov_b32 s12, 0x800000
	s_movk_i32 s13, 0x7fff
	v_readlane_b32 s37, v253, 2
	v_readlane_b32 s38, v253, 3
	v_readlane_b32 s39, v253, 4
	v_readlane_b32 s40, v253, 5
	v_readlane_b32 s41, v253, 6
	v_readlane_b32 s42, v253, 7
	v_readlane_b32 s43, v253, 8
	v_readlane_b32 s44, v253, 9
	v_readlane_b32 s45, v253, 10
	v_readlane_b32 s46, v253, 11
	v_readlane_b32 s47, v253, 12
	v_readlane_b32 s50, v253, 15
	v_readlane_b32 s51, v253, 16
	s_waitcnt vmcnt(2)
	v_ashrrev_i32_e32 v9, 31, v8
	v_mad_i64_i32 v[56:57], s[20:21], v8, s9, v[16:17]
	v_lshlrev_b64 v[52:53], 10, v[8:9]
	v_lshl_add_u64 v[56:57], v[56:57], 0, v[10:11]
	v_lshl_add_u64 v[52:53], v[12:13], 0, v[52:53]
	v_add_co_u32_e32 v56, vcc, 0x6000000, v56
	s_nop 1
	v_addc_co_u32_e32 v57, vcc, 0, v57, vcc
	global_load_dwordx4 v[52:55], v[52:53], off
	global_load_dwordx4 v[56:59], v[56:57], off offset:3072
	v_add_u32_e32 v60, s8, v8
	v_min_i32_e32 v60, s13, v60
	v_mov_b32_e32 v61, 0
	v_mad_i64_i32 v[66:67], s[20:21], v60, s9, v[16:17]
	v_lshlrev_b64 v[62:63], 10, v[60:61]
	v_lshl_add_u64 v[66:67], v[66:67], 0, v[10:11]
	v_lshl_add_u64 v[62:63], v[12:13], 0, v[62:63]
	v_add_co_u32_e32 v66, vcc, 0x6000000, v66
	s_nop 1
	v_addc_co_u32_e32 v67, vcc, 0, v67, vcc
	global_load_dwordx4 v[62:65], v[62:63], off
	global_load_dwordx4 v[66:69], v[66:67], off offset:3072
	s_waitcnt vmcnt(2)
.LBB0_586:
	v_ashrrev_i32_e32 v9, 31, v8
	s_waitcnt vmcnt(3)
	v_mov_b64_e32 v[20:21], v[52:53]
	v_mov_b64_e32 v[22:23], v[54:55]
	v_mov_b64_e32 v[24:25], v[56:57]
	v_mov_b64_e32 v[26:27], v[58:59]
	v_add_u32_e32 v60, s8, v8
	v_add_u32_e32 v60, s8, v60
	v_min_i32_e32 v60, s13, v60
	v_mov_b32_e32 v61, 0
	v_mad_i64_i32 v[56:57], s[20:21], v60, s9, v[16:17]
	v_lshlrev_b64 v[52:53], 10, v[60:61]
	v_lshl_add_u64 v[56:57], v[56:57], 0, v[10:11]
	v_lshl_add_u64 v[52:53], v[12:13], 0, v[52:53]
	v_add_co_u32_e32 v56, vcc, 0x6000000, v56
	s_nop 1
	v_addc_co_u32_e32 v57, vcc, 0, v57, vcc
	global_load_dwordx4 v[52:55], v[52:53], off
	global_load_dwordx4 v[56:59], v[56:57], off offset:3072
	v_lshlrev_b32_e32 v35, 16, v21
	v_and_b32_e32 v21, 0xffff0000, v21
	v_and_b32_e32 v39, 0xffff0000, v20
	v_lshlrev_b32_e32 v29, 16, v23
	v_and_b32_e32 v23, 0xffff0000, v23
	v_and_b32_e32 v33, 0xffff0000, v22
	v_lshlrev_b32_e32 v37, 16, v20
	v_lshlrev_b32_e32 v28, 16, v27
	v_lshlrev_b32_e32 v30, 16, v26
	v_mov_b32_e32 v42, v39
	v_mov_b32_e32 v43, v21
	v_lshlrev_b32_e32 v31, 16, v22
	v_mov_b32_e32 v40, v23
	v_mov_b32_e32 v41, v33
	v_lshlrev_b32_e32 v34, 16, v25
	v_and_b32_e32 v20, 0xffff0000, v25
	v_lshlrev_b32_e32 v36, 16, v24
	v_and_b32_e32 v38, 0xffff0000, v24
	v_mov_b32_e32 v24, v37
	v_mov_b32_e32 v25, v35
	v_mul_f32_e32 v19, 0xbfb8aa3b, v28
	v_mul_f32_e32 v44, 0xbfb8aa3b, v30
	v_pk_mul_f32 v[42:43], v[42:43], v[42:43]
	v_and_b32_e32 v22, 0xffff0000, v27
	v_and_b32_e32 v32, 0xffff0000, v26
	v_mov_b32_e32 v26, v29
	v_mov_b32_e32 v27, v31
	v_pk_mul_f32 v[40:41], v[40:41], v[40:41]
	v_exp_f32_e32 v19, v19
	v_exp_f32_e32 v44, v44
	v_pk_fma_f32 v[24:25], v[24:25], v[24:25], v[42:43]
	v_pk_fma_f32 v[26:27], v[26:27], v[26:27], v[40:41]
	v_add_f32_e32 v24, v24, v25
	v_add_f32_e32 v24, v27, v24
	v_add_f32_e32 v24, v26, v24
	v_add_f32_e32 v19, 1.0, v19
	v_add_f32_e32 v25, 1.0, v44
	v_add_f32_dpp v44, v24, v24 row_ror:8 row_mask:0xf bank_mask:0xf bound_ctrl:1
	v_rcp_f32_e32 v24, v19
	v_mul_f32_e32 v46, 0xbfb8aa3b, v34
	v_add_f32_dpp v19, v44, v44 row_ror:4 row_mask:0xf bank_mask:0xf bound_ctrl:1
	v_mul_f32_e32 v47, 0xbfb8aa3b, v20
	v_mul_f32_e32 v45, 0xbfb8aa3b, v32
	v_add_f32_dpp v19, v19, v19 row_ror:2 row_mask:0xf bank_mask:0xf bound_ctrl:1
	v_exp_f32_e32 v40, v46
	v_exp_f32_e32 v41, v47
	v_add_f32_dpp v19, v19, v19 row_ror:1 row_mask:0xf bank_mask:0xf bound_ctrl:1
	v_fmamk_f32 v19, v19, 0x3c000000, v18
	v_rcp_f32_e32 v26, v25
	v_mul_f32_e32 v25, 0x4b800000, v19
	v_cmp_gt_f32_e32 vcc, s12, v19
	v_mul_f32_e32 v49, 0xbfb8aa3b, v38
	v_exp_f32_e32 v45, v45
	v_cndmask_b32_e32 v19, v19, v25, vcc
	v_mul_f32_e32 v48, 0xbfb8aa3b, v36
	v_exp_f32_e32 v47, v49
	v_rsq_f32_e32 v19, v19
	v_exp_f32_e32 v46, v48
	v_add_f32_e32 v42, 1.0, v40
	v_add_f32_e32 v41, 1.0, v41
	v_add_f32_e32 v27, 1.0, v45
	v_rcp_f32_e32 v42, v42
	v_rcp_f32_e32 v44, v41
	v_mul_f32_e32 v50, 0xbfb8aa3b, v22
	v_add_f32_e32 v45, 1.0, v47
	v_rcp_f32_e32 v40, v27
	v_mul_f32_e32 v25, 0x45800000, v19
	v_exp_f32_e32 v50, v50
	v_add_f32_e32 v43, 1.0, v46
	v_rcp_f32_e32 v48, v45
	v_cndmask_b32_e32 v47, v19, v25, vcc
	v_rcp_f32_e32 v46, v43
	v_mov_b32_e32 v43, v47
	v_mov_b32_e32 v45, v47
	v_mov_b32_e32 v27, v47
	v_mov_b32_e32 v41, v47
	v_pk_mul_f32 v[34:35], v[42:43], v[34:35]
	v_pk_mul_f32 v[20:21], v[44:45], v[20:21]
	v_mov_b32_e32 v49, v47
	v_pk_mul_f32 v[26:27], v[26:27], v[30:31]
	v_pk_mul_f32 v[30:31], v[40:41], v[32:33]
	v_mul_f32_e32 v32, v2, v35
	v_mul_f32_e32 v21, v3, v21
	v_pk_mul_f32 v[38:39], v[48:49], v[38:39]
	v_mul_f32_e32 v32, v34, v32
	v_mul_f32_e32 v34, v20, v21
	v_add_f32_e32 v20, 1.0, v50
	v_pk_mul_f32 v[36:37], v[46:47], v[36:37]
	v_mul_f32_e32 v25, v1, v39
	v_rcp_f32_e32 v46, v20
	v_mul_f32_e32 v33, v38, v25
	v_mov_b32_e32 v25, v47
	v_pk_mul_f32 v[20:21], v[24:25], v[28:29]
	v_mul_f32_e32 v19, v0, v37
	v_mul_f32_e32 v21, v6, v21
	v_mul_f32_e32 v24, v20, v21
	v_pk_mul_f32 v[20:21], v[46:47], v[22:23]
	v_mul_f32_e32 v27, v4, v27
	v_mul_f32_e32 v21, v7, v21
	v_mul_f32_e32 v31, v5, v31
	v_mul_f32_e32 v23, v20, v21
	v_mul_f32_e32 v19, v36, v19
	v_mul_f32_e32 v26, v26, v27
	v_mul_f32_e32 v27, v30, v31
	v_cvt_pk_bf16_f32 v20, v19, v33
	v_cvt_pk_bf16_f32 v21, v32, v34
	v_cvt_pk_bf16_f32 v22, v26, v27
	v_cvt_pk_bf16_f32 v23, v24, v23
	v_lshlrev_b64 v[24:25], 11, v[8:9]
	v_add_u32_e32 v8, s8, v8
	v_cmp_lt_i32_e32 vcc, s13, v8
	v_lshl_add_u64 v[24:25], v[14:15], 0, v[24:25]
	s_or_b64 s[4:5], vcc, s[4:5]
	global_store_dwordx4 v[24:25], v[20:23], off
	s_andn2_b64 exec, exec, s[4:5]
	s_cbranch_execz .LBB0_587
; __device__ __forceinline__ void unpack8(const u32x4 w, float (&f)[8]) { f[0] = bf_lo(w.x); f[1] = bf_hi(w.x); f[2] = bf_lo(w.y); f[3] = bf_hi(w.y); f[4] = bf_lo(w.z); f[5] = bf_hi(w.z); f[6] = bf_lo(w.w); f[7] = bf_hi(w.w); }
; __device__ __forceinline__ u32x4 pack8(const float (&f)[8]) { u32x4 o; o.x = pk2(f[0], f[1]); o.y = pk2(f[2], f[3]); o.z = pk2(f[4], f[5]); o.w = pk2(f[6], f[7]); return o; }
; __device__ __forceinline__ float siluf_(float x) { return x * __builtin_amdgcn_rcpf(1.0f + __builtin_amdgcn_exp2f(x * -1.4426950408889634f)); }
; __device__ __forceinline__ void phase_gate(const Args& a) {
;     ...
;     for (int row = blockIdx.x * 8 + wave; row < M; row += gridDim.x * 8) {
;         float of8[8]; unpack8(*(const u32x4*)(of + (size_t)row * 512 + 8 * lane), of8);
;         const f32x4 o0 = {of8[0], of8[1], of8[2], of8[3]}, o1 = {of8[4], of8[5], of8[6], of8[7]};
;         float ss = (o0[0] * o0[0] + o0[1] * o0[1]) + (o0[2] * o0[2] + o0[3] * o0[3]) + (o1[0] * o1[0] + o1[1] * o1[1]) + (o1[2] * o1[2] + o1[3] * o1[3]);
;         ss = sum16(ss); const float r = rsqrtf(ss * (1.0f / 128.0f) + EPS);
;         float z[8]; unpack8(*(const u32x4*)(proj + (size_t)row * NPROJ + 1536 + 8 * lane), z);
;         float y[8];
;         y[0] = o0[0] * r * w0[0] * siluf_(z[0]); y[1] = o0[1] * r * w0[1] * siluf_(z[1]); y[2] = o0[2] * r * w0[2] * siluf_(z[2]); y[3] = o0[3] * r * w0[3] * siluf_(z[3]);
;         y[4] = o1[0] * r * w1[0] * siluf_(z[4]); y[5] = o1[1] * r * w1[1] * siluf_(z[5]); y[6] = o1[2] * r * w1[2] * siluf_(z[6]); y[7] = o1[3] * r * w1[3] * siluf_(z[7]);
;         *(u32x4*)(mix + (size_t)row * 1024 + 8 * lane) = pack8(y);
;     }
	v_ashrrev_i32_e32 v9, 31, v8
	s_waitcnt vmcnt(3)
	v_mov_b64_e32 v[20:21], v[62:63]
	v_mov_b64_e32 v[22:23], v[64:65]
	v_mov_b64_e32 v[24:25], v[66:67]
	v_mov_b64_e32 v[26:27], v[68:69]
	v_add_u32_e32 v60, s8, v8
	v_add_u32_e32 v60, s8, v60
	v_min_i32_e32 v60, s13, v60
	v_mov_b32_e32 v61, 0
	v_mad_i64_i32 v[66:67], s[20:21], v60, s9, v[16:17]
	v_lshlrev_b64 v[62:63], 10, v[60:61]
	v_lshl_add_u64 v[66:67], v[66:67], 0, v[10:11]
	v_lshl_add_u64 v[62:63], v[12:13], 0, v[62:63]
	v_add_co_u32_e32 v66, vcc, 0x6000000, v66
	s_nop 1
	v_addc_co_u32_e32 v67, vcc, 0, v67, vcc
	global_load_dwordx4 v[62:65], v[62:63], off
	global_load_dwordx4 v[66:69], v[66:67], off offset:3072
	v_lshlrev_b32_e32 v35, 16, v21
	v_and_b32_e32 v21, 0xffff0000, v21
	v_and_b32_e32 v39, 0xffff0000, v20
	v_lshlrev_b32_e32 v29, 16, v23
	v_and_b32_e32 v23, 0xffff0000, v23
	v_and_b32_e32 v33, 0xffff0000, v22
	v_lshlrev_b32_e32 v37, 16, v20
	v_lshlrev_b32_e32 v28, 16, v27
	v_lshlrev_b32_e32 v30, 16, v26
	v_mov_b32_e32 v42, v39
	v_mov_b32_e32 v43, v21
	v_lshlrev_b32_e32 v31, 16, v22
	v_mov_b32_e32 v40, v23
	v_mov_b32_e32 v41, v33
	v_lshlrev_b32_e32 v34, 16, v25
	v_and_b32_e32 v20, 0xffff0000, v25
	v_lshlrev_b32_e32 v36, 16, v24
	v_and_b32_e32 v38, 0xffff0000, v24
	v_mov_b32_e32 v24, v37
	v_mov_b32_e32 v25, v35
	v_mul_f32_e32 v19, 0xbfb8aa3b, v28
	v_mul_f32_e32 v44, 0xbfb8aa3b, v30
	v_pk_mul_f32 v[42:43], v[42:43], v[42:43]
	v_and_b32_e32 v22, 0xffff0000, v27
	v_and_b32_e32 v32, 0xffff0000, v26
	v_mov_b32_e32 v26, v29
	v_mov_b32_e32 v27, v31
	v_pk_mul_f32 v[40:41], v[40:41], v[40:41]
	v_exp_f32_e32 v19, v19
	v_exp_f32_e32 v44, v44
	v_pk_fma_f32 v[24:25], v[24:25], v[24:25], v[42:43]
	v_pk_fma_f32 v[26:27], v[26:27], v[26:27], v[40:41]
	v_add_f32_e32 v24, v24, v25
	v_add_f32_e32 v24, v27, v24
	v_add_f32_e32 v24, v26, v24
	v_add_f32_e32 v19, 1.0, v19
	v_add_f32_e32 v25, 1.0, v44
	v_add_f32_dpp v44, v24, v24 row_ror:8 row_mask:0xf bank_mask:0xf bound_ctrl:1
	v_rcp_f32_e32 v24, v19
	v_mul_f32_e32 v46, 0xbfb8aa3b, v34
	v_add_f32_dpp v19, v44, v44 row_ror:4 row_mask:0xf bank_mask:0xf bound_ctrl:1
	v_mul_f32_e32 v47, 0xbfb8aa3b, v20
	v_mul_f32_e32 v45, 0xbfb8aa3b, v32
	v_add_f32_dpp v19, v19, v19 row_ror:2 row_mask:0xf bank_mask:0xf bound_ctrl:1
	v_exp_f32_e32 v40, v46
	v_exp_f32_e32 v41, v47
	v_add_f32_dpp v19, v19, v19 row_ror:1 row_mask:0xf bank_mask:0xf bound_ctrl:1
	v_fmamk_f32 v19, v19, 0x3c000000, v18
	v_rcp_f32_e32 v26, v25
	v_mul_f32_e32 v25, 0x4b800000, v19
	v_cmp_gt_f32_e32 vcc, s12, v19
	v_mul_f32_e32 v49, 0xbfb8aa3b, v38
	v_exp_f32_e32 v45, v45
	v_cndmask_b32_e32 v19, v19, v25, vcc
	v_mul_f32_e32 v48, 0xbfb8aa3b, v36
	v_exp_f32_e32 v47, v49
	v_rsq_f32_e32 v19, v19
	v_exp_f32_e32 v46, v48
	v_add_f32_e32 v42, 1.0, v40
	v_add_f32_e32 v41, 1.0, v41
	v_add_f32_e32 v27, 1.0, v45
	v_rcp_f32_e32 v42, v42
	v_rcp_f32_e32 v44, v41
	v_mul_f32_e32 v50, 0xbfb8aa3b, v22
	v_add_f32_e32 v45, 1.0, v47
	v_rcp_f32_e32 v40, v27
	v_mul_f32_e32 v25, 0x45800000, v19
	v_exp_f32_e32 v50, v50
	v_add_f32_e32 v43, 1.0, v46
	v_rcp_f32_e32 v48, v45
	v_cndmask_b32_e32 v47, v19, v25, vcc
	v_rcp_f32_e32 v46, v43
	v_mov_b32_e32 v43, v47
	v_mov_b32_e32 v45, v47
	v_mov_b32_e32 v27, v47
	v_mov_b32_e32 v41, v47
	v_pk_mul_f32 v[34:35], v[42:43], v[34:35]
	v_pk_mul_f32 v[20:21], v[44:45], v[20:21]
	v_mov_b32_e32 v49, v47
	v_pk_mul_f32 v[26:27], v[26:27], v[30:31]
	v_pk_mul_f32 v[30:31], v[40:41], v[32:33]
	v_mul_f32_e32 v32, v2, v35
	v_mul_f32_e32 v21, v3, v21
	v_pk_mul_f32 v[38:39], v[48:49], v[38:39]
	v_mul_f32_e32 v32, v34, v32
	v_mul_f32_e32 v34, v20, v21
	v_add_f32_e32 v20, 1.0, v50
	v_pk_mul_f32 v[36:37], v[46:47], v[36:37]
	v_mul_f32_e32 v25, v1, v39
	v_rcp_f32_e32 v46, v20
	v_mul_f32_e32 v33, v38, v25
	v_mov_b32_e32 v25, v47
	v_pk_mul_f32 v[20:21], v[24:25], v[28:29]
	v_mul_f32_e32 v19, v0, v37
	v_mul_f32_e32 v21, v6, v21
	v_mul_f32_e32 v24, v20, v21
	v_pk_mul_f32 v[20:21], v[46:47], v[22:23]
	v_mul_f32_e32 v27, v4, v27
	v_mul_f32_e32 v21, v7, v21
	v_mul_f32_e32 v31, v5, v31
	v_mul_f32_e32 v23, v20, v21
	v_mul_f32_e32 v19, v36, v19
	v_mul_f32_e32 v26, v26, v27
	v_mul_f32_e32 v27, v30, v31
	v_cvt_pk_bf16_f32 v20, v19, v33
	v_cvt_pk_bf16_f32 v21, v32, v34
	v_cvt_pk_bf16_f32 v22, v26, v27
	v_cvt_pk_bf16_f32 v23, v24, v23
	v_lshlrev_b64 v[24:25], 11, v[8:9]
	v_add_u32_e32 v8, s8, v8
	v_cmp_lt_i32_e32 vcc, s13, v8
	v_lshl_add_u64 v[24:25], v[14:15], 0, v[24:25]
	s_or_b64 s[4:5], vcc, s[4:5]
	global_store_dwordx4 v[24:25], v[20:23], off
	s_andn2_b64 exec, exec, s[4:5]
	s_cbranch_execnz .LBB0_586
